# recurrence loop: a non-VALU slot ahead of the LDS instructions that sat right behind a VALU op
# speedup vs baseline: 1.0102x; 1.0102x over previous
.LBB0_682:
	s_bitcmp1_b32 s30, 0
	s_cselect_b32 s6, 0xe000, 0
	s_add_i32 s6, s6, 0
	v_add_u32_e32 v90, s6, v58
	v_sub_u32_e32 v88, v90, v61
	v_add_u32_e32 v89, s6, v86
	ds_read_b128 v[4:7], v90 offset:0x4000
	ds_read_b128 v[8:11], v90 offset:0x0
	ds_read2st64_b32 v[108:109], v89 offset0:192 offset1:193
	ds_read2st64_b64 v[100:103], v88 offset0:64 offset1:65
	ds_read_b128 v[112:115], v90 offset:0x4200
	ds_read_b128 v[96:99], v90 offset:0x200
	ds_read_b128 v[120:123], v90 offset:0x4400
	ds_read_b128 v[124:127], v90 offset:0x400
	v_mov_b32_e32 v93, v91
	s_waitcnt lgkmcnt(5)
	v_pk_mul_f32 v[0:1], v[52:53], v[4:5] op_sel_hi:[0,1]
	v_pk_fma_f32 v[0:1], v[52:53], v[6:7], v[0:1] op_sel:[1,0,0]
	v_pk_mul_f32 v[10:11], v[108:109], v[10:11] op_sel_hi:[0,1]
	ds_read_b128 v[4:7], v90 offset:0x4600
	v_add_f32_dpp v0, v0, v0 quad_perm:[1,0,3,2] row_mask:0xf bank_mask:0xf bound_ctrl:1
	v_add_f32_dpp v1, v1, v1 quad_perm:[1,0,3,2] row_mask:0xf bank_mask:0xf bound_ctrl:1
	v_pk_fma_f32 v[54:55], v[52:53], v[8:9], v[10:11]
	v_add_f32_dpp v0, v0, v0 quad_perm:[2,3,0,1] row_mask:0xf bank_mask:0xf bound_ctrl:1
	s_nop 0
	ds_read_b128 v[8:11], v90 offset:0x600
	v_add_f32_dpp v0, v0, v0 row_half_mirror row_mask:0xf bank_mask:0xf bound_ctrl:1
	ds_read2st64_b32 v[110:111], v89 offset0:194 offset1:195
	ds_read2st64_b64 v[104:107], v88 offset0:66 offset1:67
	v_add_f32_dpp v2, v0, v0 row_mirror row_mask:0xf bank_mask:0xf bound_ctrl:1
	v_add_f32_dpp v0, v0, v0 row_mirror row_mask:0xf bank_mask:0xf bound_ctrl:1
	s_nop 0
	s_waitcnt lgkmcnt(6)
	v_permlane16_swap_b32_e32 v0, v2
	v_add_f32_e32 v0, v0, v2
	v_pk_fma_f32 v[52:53], v[100:101], v[0:1], v[54:55] op_sel_hi:[1,0,1]
	v_pk_mul_f32 v[118:119], v[52:53], v[112:113] op_sel_hi:[0,1]
	v_pk_fma_f32 v[118:119], v[52:53], v[114:115], v[118:119] op_sel:[1,0,0]
	v_pk_mul_f32 v[98:99], v[108:109], v[98:99] op_sel:[1,0]
	ds_read_b128 v[112:115], v90 offset:0x4800
	v_add_f32_dpp v118, v118, v118 quad_perm:[1,0,3,2] row_mask:0xf bank_mask:0xf bound_ctrl:1
	v_add_f32_dpp v119, v119, v119 quad_perm:[1,0,3,2] row_mask:0xf bank_mask:0xf bound_ctrl:1
	v_pk_fma_f32 v[54:55], v[52:53], v[96:97], v[98:99]
	v_add_f32_dpp v118, v118, v118 quad_perm:[2,3,0,1] row_mask:0xf bank_mask:0xf bound_ctrl:1
	s_nop 0
	ds_read_b128 v[96:99], v90 offset:0x800
	v_add_f32_dpp v118, v118, v118 row_half_mirror row_mask:0xf bank_mask:0xf bound_ctrl:1
	s_nop 0
	ds_write2_b32 v93, v1, v119 offset0:0 offset1:36
	v_add_f32_dpp v2, v118, v118 row_mirror row_mask:0xf bank_mask:0xf bound_ctrl:1
	v_add_f32_dpp v118, v118, v118 row_mirror row_mask:0xf bank_mask:0xf bound_ctrl:1
	s_nop 0
	s_waitcnt lgkmcnt(4)
	v_permlane16_swap_b32_e32 v118, v2
	v_add_f32_e32 v118, v118, v2
	v_pk_fma_f32 v[52:53], v[102:103], v[118:119], v[54:55] op_sel_hi:[1,0,1]
	v_pk_mul_f32 v[0:1], v[52:53], v[120:121] op_sel_hi:[0,1]
	v_pk_fma_f32 v[0:1], v[52:53], v[122:123], v[0:1] op_sel:[1,0,0]
	v_pk_mul_f32 v[126:127], v[110:111], v[126:127] op_sel_hi:[0,1]
	ds_read_b128 v[120:123], v90 offset:0x4a00
	v_add_f32_dpp v0, v0, v0 quad_perm:[1,0,3,2] row_mask:0xf bank_mask:0xf bound_ctrl:1
	v_add_f32_dpp v1, v1, v1 quad_perm:[1,0,3,2] row_mask:0xf bank_mask:0xf bound_ctrl:1
	v_pk_fma_f32 v[54:55], v[52:53], v[124:125], v[126:127]
	v_add_f32_dpp v0, v0, v0 quad_perm:[2,3,0,1] row_mask:0xf bank_mask:0xf bound_ctrl:1
	s_nop 0
	ds_read_b128 v[124:127], v90 offset:0xa00
	v_add_f32_dpp v0, v0, v0 row_half_mirror row_mask:0xf bank_mask:0xf bound_ctrl:1
	ds_read2st64_b32 v[108:109], v89 offset0:196 offset1:197
	ds_read2st64_b64 v[100:103], v88 offset0:68 offset1:69
	v_add_f32_dpp v2, v0, v0 row_mirror row_mask:0xf bank_mask:0xf bound_ctrl:1
	v_add_f32_dpp v0, v0, v0 row_mirror row_mask:0xf bank_mask:0xf bound_ctrl:1
	s_nop 0
	s_waitcnt lgkmcnt(7)
	v_permlane16_swap_b32_e32 v0, v2
	v_add_f32_e32 v0, v0, v2
	v_pk_fma_f32 v[52:53], v[104:105], v[0:1], v[54:55] op_sel_hi:[1,0,1]
	v_pk_mul_f32 v[118:119], v[52:53], v[4:5] op_sel_hi:[0,1]
	v_pk_fma_f32 v[118:119], v[52:53], v[6:7], v[118:119] op_sel:[1,0,0]
	v_pk_mul_f32 v[10:11], v[110:111], v[10:11] op_sel:[1,0]
	ds_read_b128 v[4:7], v90 offset:0x4c00
	v_add_f32_dpp v118, v118, v118 quad_perm:[1,0,3,2] row_mask:0xf bank_mask:0xf bound_ctrl:1
	v_add_f32_dpp v119, v119, v119 quad_perm:[1,0,3,2] row_mask:0xf bank_mask:0xf bound_ctrl:1
	v_pk_fma_f32 v[54:55], v[52:53], v[8:9], v[10:11]
	v_add_f32_dpp v118, v118, v118 quad_perm:[2,3,0,1] row_mask:0xf bank_mask:0xf bound_ctrl:1
	s_nop 0
	ds_read_b128 v[8:11], v90 offset:0xc00
	v_add_f32_dpp v118, v118, v118 row_half_mirror row_mask:0xf bank_mask:0xf bound_ctrl:1
	s_nop 0
	ds_write2_b32 v93, v1, v119 offset0:72 offset1:108
	v_add_f32_dpp v2, v118, v118 row_mirror row_mask:0xf bank_mask:0xf bound_ctrl:1
	v_add_f32_dpp v118, v118, v118 row_mirror row_mask:0xf bank_mask:0xf bound_ctrl:1
	s_nop 0
	s_waitcnt lgkmcnt(4)
	v_permlane16_swap_b32_e32 v118, v2
	v_add_f32_e32 v118, v118, v2
	v_pk_fma_f32 v[52:53], v[106:107], v[118:119], v[54:55] op_sel_hi:[1,0,1]
	v_pk_mul_f32 v[0:1], v[52:53], v[112:113] op_sel_hi:[0,1]
	v_pk_fma_f32 v[0:1], v[52:53], v[114:115], v[0:1] op_sel:[1,0,0]
	v_pk_mul_f32 v[98:99], v[108:109], v[98:99] op_sel_hi:[0,1]
	ds_read_b128 v[112:115], v90 offset:0x4e00
	v_add_f32_dpp v0, v0, v0 quad_perm:[1,0,3,2] row_mask:0xf bank_mask:0xf bound_ctrl:1
	v_add_f32_dpp v1, v1, v1 quad_perm:[1,0,3,2] row_mask:0xf bank_mask:0xf bound_ctrl:1
	v_pk_fma_f32 v[54:55], v[52:53], v[96:97], v[98:99]
	v_add_f32_dpp v0, v0, v0 quad_perm:[2,3,0,1] row_mask:0xf bank_mask:0xf bound_ctrl:1
	s_nop 0
	ds_read_b128 v[96:99], v90 offset:0xe00
	v_add_f32_dpp v0, v0, v0 row_half_mirror row_mask:0xf bank_mask:0xf bound_ctrl:1
	ds_read2st64_b32 v[110:111], v89 offset0:198 offset1:199
	ds_read2st64_b64 v[104:107], v88 offset0:70 offset1:71
	v_add_f32_dpp v2, v0, v0 row_mirror row_mask:0xf bank_mask:0xf bound_ctrl:1
	v_add_f32_dpp v0, v0, v0 row_mirror row_mask:0xf bank_mask:0xf bound_ctrl:1
	s_nop 0
	s_waitcnt lgkmcnt(7)
	v_permlane16_swap_b32_e32 v0, v2
	v_add_f32_e32 v0, v0, v2
	v_pk_fma_f32 v[52:53], v[100:101], v[0:1], v[54:55] op_sel_hi:[1,0,1]
	v_pk_mul_f32 v[118:119], v[52:53], v[120:121] op_sel_hi:[0,1]
	v_pk_fma_f32 v[118:119], v[52:53], v[122:123], v[118:119] op_sel:[1,0,0]
	v_pk_mul_f32 v[126:127], v[108:109], v[126:127] op_sel:[1,0]
	ds_read_b128 v[120:123], v90 offset:0x5000
	v_add_f32_dpp v118, v118, v118 quad_perm:[1,0,3,2] row_mask:0xf bank_mask:0xf bound_ctrl:1
	v_add_f32_dpp v119, v119, v119 quad_perm:[1,0,3,2] row_mask:0xf bank_mask:0xf bound_ctrl:1
	v_pk_fma_f32 v[54:55], v[52:53], v[124:125], v[126:127]
	v_add_f32_dpp v118, v118, v118 quad_perm:[2,3,0,1] row_mask:0xf bank_mask:0xf bound_ctrl:1
	s_nop 0
	ds_read_b128 v[124:127], v90 offset:0x1000
	v_add_f32_dpp v118, v118, v118 row_half_mirror row_mask:0xf bank_mask:0xf bound_ctrl:1
	s_nop 0
	ds_write2_b32 v93, v1, v119 offset0:144 offset1:180
	v_add_f32_dpp v2, v118, v118 row_mirror row_mask:0xf bank_mask:0xf bound_ctrl:1
	v_add_f32_dpp v118, v118, v118 row_mirror row_mask:0xf bank_mask:0xf bound_ctrl:1
	s_nop 0
	s_waitcnt lgkmcnt(4)
	v_permlane16_swap_b32_e32 v118, v2
	v_add_f32_e32 v118, v118, v2
	v_pk_fma_f32 v[52:53], v[102:103], v[118:119], v[54:55] op_sel_hi:[1,0,1]
	v_pk_mul_f32 v[0:1], v[52:53], v[4:5] op_sel_hi:[0,1]
	v_pk_fma_f32 v[0:1], v[52:53], v[6:7], v[0:1] op_sel:[1,0,0]
	v_pk_mul_f32 v[10:11], v[110:111], v[10:11] op_sel_hi:[0,1]
	ds_read_b128 v[4:7], v90 offset:0x5200
	v_add_f32_dpp v0, v0, v0 quad_perm:[1,0,3,2] row_mask:0xf bank_mask:0xf bound_ctrl:1
	v_add_f32_dpp v1, v1, v1 quad_perm:[1,0,3,2] row_mask:0xf bank_mask:0xf bound_ctrl:1
	v_pk_fma_f32 v[54:55], v[52:53], v[8:9], v[10:11]
	v_add_f32_dpp v0, v0, v0 quad_perm:[2,3,0,1] row_mask:0xf bank_mask:0xf bound_ctrl:1
	s_nop 0
	ds_read_b128 v[8:11], v90 offset:0x1200
	v_add_f32_dpp v0, v0, v0 row_half_mirror row_mask:0xf bank_mask:0xf bound_ctrl:1
	ds_read2st64_b32 v[108:109], v89 offset0:200 offset1:201
	ds_read2st64_b64 v[100:103], v88 offset0:72 offset1:73
	v_add_f32_dpp v2, v0, v0 row_mirror row_mask:0xf bank_mask:0xf bound_ctrl:1
	v_add_f32_dpp v0, v0, v0 row_mirror row_mask:0xf bank_mask:0xf bound_ctrl:1
	s_nop 0
	s_waitcnt lgkmcnt(7)
	v_permlane16_swap_b32_e32 v0, v2
	v_add_f32_e32 v0, v0, v2
	v_pk_fma_f32 v[52:53], v[104:105], v[0:1], v[54:55] op_sel_hi:[1,0,1]
	v_pk_mul_f32 v[118:119], v[52:53], v[112:113] op_sel_hi:[0,1]
	v_pk_fma_f32 v[118:119], v[52:53], v[114:115], v[118:119] op_sel:[1,0,0]
	v_pk_mul_f32 v[98:99], v[110:111], v[98:99] op_sel:[1,0]
	ds_read_b128 v[112:115], v90 offset:0x5400
	v_add_f32_dpp v118, v118, v118 quad_perm:[1,0,3,2] row_mask:0xf bank_mask:0xf bound_ctrl:1
	v_add_f32_dpp v119, v119, v119 quad_perm:[1,0,3,2] row_mask:0xf bank_mask:0xf bound_ctrl:1
	v_pk_fma_f32 v[54:55], v[52:53], v[96:97], v[98:99]
	v_add_f32_dpp v118, v118, v118 quad_perm:[2,3,0,1] row_mask:0xf bank_mask:0xf bound_ctrl:1
	s_nop 0
	ds_read_b128 v[96:99], v90 offset:0x1400
	v_add_f32_dpp v118, v118, v118 row_half_mirror row_mask:0xf bank_mask:0xf bound_ctrl:1
	s_nop 0
	ds_write2_b32 v93, v1, v119 offset0:216 offset1:252
	v_add_f32_dpp v2, v118, v118 row_mirror row_mask:0xf bank_mask:0xf bound_ctrl:1
	v_add_f32_dpp v118, v118, v118 row_mirror row_mask:0xf bank_mask:0xf bound_ctrl:1
	s_nop 0
	s_waitcnt lgkmcnt(4)
	v_permlane16_swap_b32_e32 v118, v2
	v_add_f32_e32 v118, v118, v2
	v_pk_fma_f32 v[52:53], v[106:107], v[118:119], v[54:55] op_sel_hi:[1,0,1]
	v_pk_mul_f32 v[0:1], v[52:53], v[120:121] op_sel_hi:[0,1]
	v_pk_fma_f32 v[0:1], v[52:53], v[122:123], v[0:1] op_sel:[1,0,0]
	v_pk_mul_f32 v[126:127], v[108:109], v[126:127] op_sel_hi:[0,1]
	ds_read_b128 v[120:123], v90 offset:0x5600
	v_add_f32_dpp v0, v0, v0 quad_perm:[1,0,3,2] row_mask:0xf bank_mask:0xf bound_ctrl:1
	v_add_f32_dpp v1, v1, v1 quad_perm:[1,0,3,2] row_mask:0xf bank_mask:0xf bound_ctrl:1
	v_pk_fma_f32 v[54:55], v[52:53], v[124:125], v[126:127]
	v_add_f32_dpp v0, v0, v0 quad_perm:[2,3,0,1] row_mask:0xf bank_mask:0xf bound_ctrl:1
	s_nop 0
	ds_read_b128 v[124:127], v90 offset:0x1600
	v_add_f32_dpp v0, v0, v0 row_half_mirror row_mask:0xf bank_mask:0xf bound_ctrl:1
	ds_read2st64_b32 v[110:111], v89 offset0:202 offset1:203
	ds_read2st64_b64 v[104:107], v88 offset0:74 offset1:75
	v_add_f32_dpp v2, v0, v0 row_mirror row_mask:0xf bank_mask:0xf bound_ctrl:1
	v_add_f32_dpp v0, v0, v0 row_mirror row_mask:0xf bank_mask:0xf bound_ctrl:1
	v_add_u32_e32 v93, 0x480, v93
	s_waitcnt lgkmcnt(7)
	v_permlane16_swap_b32_e32 v0, v2
	v_add_f32_e32 v0, v0, v2
	v_pk_fma_f32 v[52:53], v[100:101], v[0:1], v[54:55] op_sel_hi:[1,0,1]
	v_pk_mul_f32 v[118:119], v[52:53], v[4:5] op_sel_hi:[0,1]
	v_pk_fma_f32 v[118:119], v[52:53], v[6:7], v[118:119] op_sel:[1,0,0]
	v_pk_mul_f32 v[10:11], v[108:109], v[10:11] op_sel:[1,0]
	ds_read_b128 v[4:7], v90 offset:0x5800
	v_add_f32_dpp v118, v118, v118 quad_perm:[1,0,3,2] row_mask:0xf bank_mask:0xf bound_ctrl:1
	v_add_f32_dpp v119, v119, v119 quad_perm:[1,0,3,2] row_mask:0xf bank_mask:0xf bound_ctrl:1
	v_pk_fma_f32 v[54:55], v[52:53], v[8:9], v[10:11]
	v_add_f32_dpp v118, v118, v118 quad_perm:[2,3,0,1] row_mask:0xf bank_mask:0xf bound_ctrl:1
	s_nop 0
	ds_read_b128 v[8:11], v90 offset:0x1800
	v_add_f32_dpp v118, v118, v118 row_half_mirror row_mask:0xf bank_mask:0xf bound_ctrl:1
	s_nop 0
	ds_write2_b32 v93, v1, v119 offset0:0 offset1:36
	v_add_f32_dpp v2, v118, v118 row_mirror row_mask:0xf bank_mask:0xf bound_ctrl:1
	v_add_f32_dpp v118, v118, v118 row_mirror row_mask:0xf bank_mask:0xf bound_ctrl:1
	s_nop 0
	s_waitcnt lgkmcnt(4)
	v_permlane16_swap_b32_e32 v118, v2
	v_add_f32_e32 v118, v118, v2
	v_pk_fma_f32 v[52:53], v[102:103], v[118:119], v[54:55] op_sel_hi:[1,0,1]
	v_pk_mul_f32 v[0:1], v[52:53], v[112:113] op_sel_hi:[0,1]
	v_pk_fma_f32 v[0:1], v[52:53], v[114:115], v[0:1] op_sel:[1,0,0]
	v_pk_mul_f32 v[98:99], v[110:111], v[98:99] op_sel_hi:[0,1]
	ds_read_b128 v[112:115], v90 offset:0x5a00
	v_add_f32_dpp v0, v0, v0 quad_perm:[1,0,3,2] row_mask:0xf bank_mask:0xf bound_ctrl:1
	v_add_f32_dpp v1, v1, v1 quad_perm:[1,0,3,2] row_mask:0xf bank_mask:0xf bound_ctrl:1
	v_pk_fma_f32 v[54:55], v[52:53], v[96:97], v[98:99]
	v_add_f32_dpp v0, v0, v0 quad_perm:[2,3,0,1] row_mask:0xf bank_mask:0xf bound_ctrl:1
	s_nop 0
	ds_read_b128 v[96:99], v90 offset:0x1a00
	v_add_f32_dpp v0, v0, v0 row_half_mirror row_mask:0xf bank_mask:0xf bound_ctrl:1
	ds_read2st64_b32 v[108:109], v89 offset0:204 offset1:205
	ds_read2st64_b64 v[100:103], v88 offset0:76 offset1:77
	v_add_f32_dpp v2, v0, v0 row_mirror row_mask:0xf bank_mask:0xf bound_ctrl:1
	v_add_f32_dpp v0, v0, v0 row_mirror row_mask:0xf bank_mask:0xf bound_ctrl:1
	s_nop 0
	s_waitcnt lgkmcnt(7)
	v_permlane16_swap_b32_e32 v0, v2
	v_add_f32_e32 v0, v0, v2
	v_pk_fma_f32 v[52:53], v[104:105], v[0:1], v[54:55] op_sel_hi:[1,0,1]
	v_pk_mul_f32 v[118:119], v[52:53], v[120:121] op_sel_hi:[0,1]
	v_pk_fma_f32 v[118:119], v[52:53], v[122:123], v[118:119] op_sel:[1,0,0]
	v_pk_mul_f32 v[126:127], v[110:111], v[126:127] op_sel:[1,0]
	ds_read_b128 v[120:123], v90 offset:0x5c00
	v_add_f32_dpp v118, v118, v118 quad_perm:[1,0,3,2] row_mask:0xf bank_mask:0xf bound_ctrl:1
	v_add_f32_dpp v119, v119, v119 quad_perm:[1,0,3,2] row_mask:0xf bank_mask:0xf bound_ctrl:1
	v_pk_fma_f32 v[54:55], v[52:53], v[124:125], v[126:127]
	v_add_f32_dpp v118, v118, v118 quad_perm:[2,3,0,1] row_mask:0xf bank_mask:0xf bound_ctrl:1
	s_nop 0
	ds_read_b128 v[124:127], v90 offset:0x1c00
	v_add_f32_dpp v118, v118, v118 row_half_mirror row_mask:0xf bank_mask:0xf bound_ctrl:1
	s_nop 0
	ds_write2_b32 v93, v1, v119 offset0:72 offset1:108
	v_add_f32_dpp v2, v118, v118 row_mirror row_mask:0xf bank_mask:0xf bound_ctrl:1
	v_add_f32_dpp v118, v118, v118 row_mirror row_mask:0xf bank_mask:0xf bound_ctrl:1
	s_nop 0
	s_waitcnt lgkmcnt(4)
	v_permlane16_swap_b32_e32 v118, v2
	v_add_f32_e32 v118, v118, v2
	v_pk_fma_f32 v[52:53], v[106:107], v[118:119], v[54:55] op_sel_hi:[1,0,1]
	v_pk_mul_f32 v[0:1], v[52:53], v[4:5] op_sel_hi:[0,1]
	v_pk_fma_f32 v[0:1], v[52:53], v[6:7], v[0:1] op_sel:[1,0,0]
	v_pk_mul_f32 v[10:11], v[108:109], v[10:11] op_sel_hi:[0,1]
	ds_read_b128 v[4:7], v90 offset:0x5e00
	v_add_f32_dpp v0, v0, v0 quad_perm:[1,0,3,2] row_mask:0xf bank_mask:0xf bound_ctrl:1
	v_add_f32_dpp v1, v1, v1 quad_perm:[1,0,3,2] row_mask:0xf bank_mask:0xf bound_ctrl:1
	v_pk_fma_f32 v[54:55], v[52:53], v[8:9], v[10:11]
	v_add_f32_dpp v0, v0, v0 quad_perm:[2,3,0,1] row_mask:0xf bank_mask:0xf bound_ctrl:1
	s_nop 0
	ds_read_b128 v[8:11], v90 offset:0x1e00
	v_add_f32_dpp v0, v0, v0 row_half_mirror row_mask:0xf bank_mask:0xf bound_ctrl:1
	ds_read2st64_b32 v[110:111], v89 offset0:206 offset1:207
	ds_read2st64_b64 v[104:107], v88 offset0:78 offset1:79
	v_add_f32_dpp v2, v0, v0 row_mirror row_mask:0xf bank_mask:0xf bound_ctrl:1
	v_add_f32_dpp v0, v0, v0 row_mirror row_mask:0xf bank_mask:0xf bound_ctrl:1
	s_nop 0
	s_waitcnt lgkmcnt(7)
	v_permlane16_swap_b32_e32 v0, v2
	v_add_f32_e32 v0, v0, v2
	v_pk_fma_f32 v[52:53], v[100:101], v[0:1], v[54:55] op_sel_hi:[1,0,1]
	v_pk_mul_f32 v[118:119], v[52:53], v[112:113] op_sel_hi:[0,1]
	v_pk_fma_f32 v[118:119], v[52:53], v[114:115], v[118:119] op_sel:[1,0,0]
	v_pk_mul_f32 v[98:99], v[108:109], v[98:99] op_sel:[1,0]
	ds_read_b128 v[112:115], v90 offset:0x6000
	v_add_f32_dpp v118, v118, v118 quad_perm:[1,0,3,2] row_mask:0xf bank_mask:0xf bound_ctrl:1
	v_add_f32_dpp v119, v119, v119 quad_perm:[1,0,3,2] row_mask:0xf bank_mask:0xf bound_ctrl:1
	v_pk_fma_f32 v[54:55], v[52:53], v[96:97], v[98:99]
	v_add_f32_dpp v118, v118, v118 quad_perm:[2,3,0,1] row_mask:0xf bank_mask:0xf bound_ctrl:1
	s_nop 0
	ds_read_b128 v[96:99], v90 offset:0x2000
	v_add_f32_dpp v118, v118, v118 row_half_mirror row_mask:0xf bank_mask:0xf bound_ctrl:1
	s_nop 0
	ds_write2_b32 v93, v1, v119 offset0:144 offset1:180
	v_add_f32_dpp v2, v118, v118 row_mirror row_mask:0xf bank_mask:0xf bound_ctrl:1
	v_add_f32_dpp v118, v118, v118 row_mirror row_mask:0xf bank_mask:0xf bound_ctrl:1
	s_nop 0
	s_waitcnt lgkmcnt(4)
	v_permlane16_swap_b32_e32 v118, v2
	v_add_f32_e32 v118, v118, v2
	v_pk_fma_f32 v[52:53], v[102:103], v[118:119], v[54:55] op_sel_hi:[1,0,1]
	v_pk_mul_f32 v[0:1], v[52:53], v[120:121] op_sel_hi:[0,1]
	v_pk_fma_f32 v[0:1], v[52:53], v[122:123], v[0:1] op_sel:[1,0,0]
	v_pk_mul_f32 v[126:127], v[110:111], v[126:127] op_sel_hi:[0,1]
	ds_read_b128 v[120:123], v90 offset:0x6200
	v_add_f32_dpp v0, v0, v0 quad_perm:[1,0,3,2] row_mask:0xf bank_mask:0xf bound_ctrl:1
	v_add_f32_dpp v1, v1, v1 quad_perm:[1,0,3,2] row_mask:0xf bank_mask:0xf bound_ctrl:1
	v_pk_fma_f32 v[54:55], v[52:53], v[124:125], v[126:127]
	v_add_f32_dpp v0, v0, v0 quad_perm:[2,3,0,1] row_mask:0xf bank_mask:0xf bound_ctrl:1
	s_nop 0
	ds_read_b128 v[124:127], v90 offset:0x2200
	v_add_f32_dpp v0, v0, v0 row_half_mirror row_mask:0xf bank_mask:0xf bound_ctrl:1
	ds_read2st64_b32 v[108:109], v89 offset0:208 offset1:209
	ds_read2st64_b64 v[100:103], v88 offset0:80 offset1:81
	v_add_f32_dpp v2, v0, v0 row_mirror row_mask:0xf bank_mask:0xf bound_ctrl:1
	v_add_f32_dpp v0, v0, v0 row_mirror row_mask:0xf bank_mask:0xf bound_ctrl:1
	s_nop 0
	s_waitcnt lgkmcnt(7)
	v_permlane16_swap_b32_e32 v0, v2
	v_add_f32_e32 v0, v0, v2
	v_pk_fma_f32 v[52:53], v[104:105], v[0:1], v[54:55] op_sel_hi:[1,0,1]
	v_pk_mul_f32 v[118:119], v[52:53], v[4:5] op_sel_hi:[0,1]
	v_pk_fma_f32 v[118:119], v[52:53], v[6:7], v[118:119] op_sel:[1,0,0]
	v_pk_mul_f32 v[10:11], v[110:111], v[10:11] op_sel:[1,0]
	ds_read_b128 v[4:7], v90 offset:0x6400
	v_add_f32_dpp v118, v118, v118 quad_perm:[1,0,3,2] row_mask:0xf bank_mask:0xf bound_ctrl:1
	v_add_f32_dpp v119, v119, v119 quad_perm:[1,0,3,2] row_mask:0xf bank_mask:0xf bound_ctrl:1
	v_pk_fma_f32 v[54:55], v[52:53], v[8:9], v[10:11]
	v_add_f32_dpp v118, v118, v118 quad_perm:[2,3,0,1] row_mask:0xf bank_mask:0xf bound_ctrl:1
	s_nop 0
	ds_read_b128 v[8:11], v90 offset:0x2400
	v_add_f32_dpp v118, v118, v118 row_half_mirror row_mask:0xf bank_mask:0xf bound_ctrl:1
	s_nop 0
	ds_write2_b32 v93, v1, v119 offset0:216 offset1:252
	v_add_f32_dpp v2, v118, v118 row_mirror row_mask:0xf bank_mask:0xf bound_ctrl:1
	v_add_f32_dpp v118, v118, v118 row_mirror row_mask:0xf bank_mask:0xf bound_ctrl:1
	s_nop 0
	s_waitcnt lgkmcnt(4)
	v_permlane16_swap_b32_e32 v118, v2
	v_add_f32_e32 v118, v118, v2
	v_pk_fma_f32 v[52:53], v[106:107], v[118:119], v[54:55] op_sel_hi:[1,0,1]
	s_cmp_eq_u32 s88, 0x800000
	s_cbranch_scc1 .LBB0_684
	v_pk_mul_f32 v[0:1], v[52:53], v[112:113] op_sel_hi:[0,1]
	v_pk_fma_f32 v[0:1], v[52:53], v[114:115], v[0:1] op_sel:[1,0,0]
	v_pk_mul_f32 v[98:99], v[108:109], v[98:99] op_sel_hi:[0,1]
	ds_read_b128 v[112:115], v90 offset:0x6600
	v_add_f32_dpp v0, v0, v0 quad_perm:[1,0,3,2] row_mask:0xf bank_mask:0xf bound_ctrl:1
	v_add_f32_dpp v1, v1, v1 quad_perm:[1,0,3,2] row_mask:0xf bank_mask:0xf bound_ctrl:1
	v_pk_fma_f32 v[54:55], v[52:53], v[96:97], v[98:99]
	v_add_f32_dpp v0, v0, v0 quad_perm:[2,3,0,1] row_mask:0xf bank_mask:0xf bound_ctrl:1
	s_nop 0
	ds_read_b128 v[96:99], v90 offset:0x2600
	v_add_f32_dpp v0, v0, v0 row_half_mirror row_mask:0xf bank_mask:0xf bound_ctrl:1
	ds_read2st64_b32 v[110:111], v89 offset0:210 offset1:211
	ds_read2st64_b64 v[104:107], v88 offset0:82 offset1:83
	v_add_f32_dpp v2, v0, v0 row_mirror row_mask:0xf bank_mask:0xf bound_ctrl:1
	v_add_f32_dpp v0, v0, v0 row_mirror row_mask:0xf bank_mask:0xf bound_ctrl:1
	v_add_u32_e32 v93, 0x480, v93
	s_waitcnt lgkmcnt(7)
	v_permlane16_swap_b32_e32 v0, v2
	v_add_f32_e32 v0, v0, v2
	v_pk_fma_f32 v[52:53], v[100:101], v[0:1], v[54:55] op_sel_hi:[1,0,1]
	v_pk_mul_f32 v[118:119], v[52:53], v[120:121] op_sel_hi:[0,1]
	v_pk_fma_f32 v[118:119], v[52:53], v[122:123], v[118:119] op_sel:[1,0,0]
	v_pk_mul_f32 v[126:127], v[108:109], v[126:127] op_sel:[1,0]
	ds_read_b128 v[120:123], v90 offset:0x6800
	v_add_f32_dpp v118, v118, v118 quad_perm:[1,0,3,2] row_mask:0xf bank_mask:0xf bound_ctrl:1
	v_add_f32_dpp v119, v119, v119 quad_perm:[1,0,3,2] row_mask:0xf bank_mask:0xf bound_ctrl:1
	v_pk_fma_f32 v[54:55], v[52:53], v[124:125], v[126:127]
	v_add_f32_dpp v118, v118, v118 quad_perm:[2,3,0,1] row_mask:0xf bank_mask:0xf bound_ctrl:1
	s_nop 0
	ds_read_b128 v[124:127], v90 offset:0x2800
	v_add_f32_dpp v118, v118, v118 row_half_mirror row_mask:0xf bank_mask:0xf bound_ctrl:1
	s_nop 0
	ds_write2_b32 v93, v1, v119 offset0:0 offset1:36
	v_add_f32_dpp v2, v118, v118 row_mirror row_mask:0xf bank_mask:0xf bound_ctrl:1
	v_add_f32_dpp v118, v118, v118 row_mirror row_mask:0xf bank_mask:0xf bound_ctrl:1
	s_nop 0
	s_waitcnt lgkmcnt(4)
	v_permlane16_swap_b32_e32 v118, v2
	v_add_f32_e32 v118, v118, v2
	v_pk_fma_f32 v[52:53], v[102:103], v[118:119], v[54:55] op_sel_hi:[1,0,1]
	v_pk_mul_f32 v[0:1], v[52:53], v[4:5] op_sel_hi:[0,1]
	v_pk_fma_f32 v[0:1], v[52:53], v[6:7], v[0:1] op_sel:[1,0,0]
	v_pk_mul_f32 v[10:11], v[110:111], v[10:11] op_sel_hi:[0,1]
	ds_read_b128 v[4:7], v90 offset:0x6a00
	v_add_f32_dpp v0, v0, v0 quad_perm:[1,0,3,2] row_mask:0xf bank_mask:0xf bound_ctrl:1
	v_add_f32_dpp v1, v1, v1 quad_perm:[1,0,3,2] row_mask:0xf bank_mask:0xf bound_ctrl:1
	v_pk_fma_f32 v[54:55], v[52:53], v[8:9], v[10:11]
	v_add_f32_dpp v0, v0, v0 quad_perm:[2,3,0,1] row_mask:0xf bank_mask:0xf bound_ctrl:1
	s_nop 0
	ds_read_b128 v[8:11], v90 offset:0x2a00
	v_add_f32_dpp v0, v0, v0 row_half_mirror row_mask:0xf bank_mask:0xf bound_ctrl:1
	ds_read2st64_b32 v[108:109], v89 offset0:212 offset1:213
	ds_read2st64_b64 v[100:103], v88 offset0:84 offset1:85
	v_add_f32_dpp v2, v0, v0 row_mirror row_mask:0xf bank_mask:0xf bound_ctrl:1
	v_add_f32_dpp v0, v0, v0 row_mirror row_mask:0xf bank_mask:0xf bound_ctrl:1
	s_nop 0
	s_waitcnt lgkmcnt(7)
	v_permlane16_swap_b32_e32 v0, v2
	v_add_f32_e32 v0, v0, v2
	v_pk_fma_f32 v[52:53], v[104:105], v[0:1], v[54:55] op_sel_hi:[1,0,1]
	v_pk_mul_f32 v[118:119], v[52:53], v[112:113] op_sel_hi:[0,1]
	v_pk_fma_f32 v[118:119], v[52:53], v[114:115], v[118:119] op_sel:[1,0,0]
	v_pk_mul_f32 v[98:99], v[110:111], v[98:99] op_sel:[1,0]
	ds_read_b128 v[112:115], v90 offset:0x6c00
	v_add_f32_dpp v118, v118, v118 quad_perm:[1,0,3,2] row_mask:0xf bank_mask:0xf bound_ctrl:1
	v_add_f32_dpp v119, v119, v119 quad_perm:[1,0,3,2] row_mask:0xf bank_mask:0xf bound_ctrl:1
	v_pk_fma_f32 v[54:55], v[52:53], v[96:97], v[98:99]
	v_add_f32_dpp v118, v118, v118 quad_perm:[2,3,0,1] row_mask:0xf bank_mask:0xf bound_ctrl:1
	s_nop 0
	ds_read_b128 v[96:99], v90 offset:0x2c00
	v_add_f32_dpp v118, v118, v118 row_half_mirror row_mask:0xf bank_mask:0xf bound_ctrl:1
	s_nop 0
	ds_write2_b32 v93, v1, v119 offset0:72 offset1:108
	v_add_f32_dpp v2, v118, v118 row_mirror row_mask:0xf bank_mask:0xf bound_ctrl:1
	v_add_f32_dpp v118, v118, v118 row_mirror row_mask:0xf bank_mask:0xf bound_ctrl:1
	s_nop 0
	s_waitcnt lgkmcnt(4)
	v_permlane16_swap_b32_e32 v118, v2
	v_add_f32_e32 v118, v118, v2
	v_pk_fma_f32 v[52:53], v[106:107], v[118:119], v[54:55] op_sel_hi:[1,0,1]
	v_pk_mul_f32 v[0:1], v[52:53], v[120:121] op_sel_hi:[0,1]
	v_pk_fma_f32 v[0:1], v[52:53], v[122:123], v[0:1] op_sel:[1,0,0]
	v_pk_mul_f32 v[126:127], v[108:109], v[126:127] op_sel_hi:[0,1]
	ds_read_b128 v[120:123], v90 offset:0x6e00
	v_add_f32_dpp v0, v0, v0 quad_perm:[1,0,3,2] row_mask:0xf bank_mask:0xf bound_ctrl:1
	v_add_f32_dpp v1, v1, v1 quad_perm:[1,0,3,2] row_mask:0xf bank_mask:0xf bound_ctrl:1
	v_pk_fma_f32 v[54:55], v[52:53], v[124:125], v[126:127]
	v_add_f32_dpp v0, v0, v0 quad_perm:[2,3,0,1] row_mask:0xf bank_mask:0xf bound_ctrl:1
	s_nop 0
	ds_read_b128 v[124:127], v90 offset:0x2e00
	v_add_f32_dpp v0, v0, v0 row_half_mirror row_mask:0xf bank_mask:0xf bound_ctrl:1
	ds_read2st64_b32 v[110:111], v89 offset0:214 offset1:215
	ds_read2st64_b64 v[104:107], v88 offset0:86 offset1:87
	v_add_f32_dpp v2, v0, v0 row_mirror row_mask:0xf bank_mask:0xf bound_ctrl:1
	v_add_f32_dpp v0, v0, v0 row_mirror row_mask:0xf bank_mask:0xf bound_ctrl:1
	s_nop 0
	s_waitcnt lgkmcnt(7)
	v_permlane16_swap_b32_e32 v0, v2
	v_add_f32_e32 v0, v0, v2
	v_pk_fma_f32 v[52:53], v[100:101], v[0:1], v[54:55] op_sel_hi:[1,0,1]
	v_pk_mul_f32 v[118:119], v[52:53], v[4:5] op_sel_hi:[0,1]
	v_pk_fma_f32 v[118:119], v[52:53], v[6:7], v[118:119] op_sel:[1,0,0]
	v_pk_mul_f32 v[10:11], v[108:109], v[10:11] op_sel:[1,0]
	ds_read_b128 v[4:7], v90 offset:0x7000
	v_add_f32_dpp v118, v118, v118 quad_perm:[1,0,3,2] row_mask:0xf bank_mask:0xf bound_ctrl:1
	v_add_f32_dpp v119, v119, v119 quad_perm:[1,0,3,2] row_mask:0xf bank_mask:0xf bound_ctrl:1
	v_pk_fma_f32 v[54:55], v[52:53], v[8:9], v[10:11]
	v_add_f32_dpp v118, v118, v118 quad_perm:[2,3,0,1] row_mask:0xf bank_mask:0xf bound_ctrl:1
	s_nop 0
	ds_read_b128 v[8:11], v90 offset:0x3000
	v_add_f32_dpp v118, v118, v118 row_half_mirror row_mask:0xf bank_mask:0xf bound_ctrl:1
	s_nop 0
	ds_write2_b32 v93, v1, v119 offset0:144 offset1:180
	v_add_f32_dpp v2, v118, v118 row_mirror row_mask:0xf bank_mask:0xf bound_ctrl:1
	v_add_f32_dpp v118, v118, v118 row_mirror row_mask:0xf bank_mask:0xf bound_ctrl:1
	s_nop 0
	s_waitcnt lgkmcnt(4)
	v_permlane16_swap_b32_e32 v118, v2
	v_add_f32_e32 v118, v118, v2
	v_pk_fma_f32 v[52:53], v[102:103], v[118:119], v[54:55] op_sel_hi:[1,0,1]
	v_pk_mul_f32 v[0:1], v[52:53], v[112:113] op_sel_hi:[0,1]
	v_pk_fma_f32 v[0:1], v[52:53], v[114:115], v[0:1] op_sel:[1,0,0]
	v_pk_mul_f32 v[98:99], v[110:111], v[98:99] op_sel_hi:[0,1]
	ds_read_b128 v[112:115], v90 offset:0x7200
	v_add_f32_dpp v0, v0, v0 quad_perm:[1,0,3,2] row_mask:0xf bank_mask:0xf bound_ctrl:1
	v_add_f32_dpp v1, v1, v1 quad_perm:[1,0,3,2] row_mask:0xf bank_mask:0xf bound_ctrl:1
	v_pk_fma_f32 v[54:55], v[52:53], v[96:97], v[98:99]
	v_add_f32_dpp v0, v0, v0 quad_perm:[2,3,0,1] row_mask:0xf bank_mask:0xf bound_ctrl:1
	s_nop 0
	ds_read_b128 v[96:99], v90 offset:0x3200
	v_add_f32_dpp v0, v0, v0 row_half_mirror row_mask:0xf bank_mask:0xf bound_ctrl:1
	ds_read2st64_b32 v[108:109], v89 offset0:216 offset1:217
	ds_read2st64_b64 v[100:103], v88 offset0:88 offset1:89
	v_add_f32_dpp v2, v0, v0 row_mirror row_mask:0xf bank_mask:0xf bound_ctrl:1
	v_add_f32_dpp v0, v0, v0 row_mirror row_mask:0xf bank_mask:0xf bound_ctrl:1
	s_nop 0
	s_waitcnt lgkmcnt(7)
	v_permlane16_swap_b32_e32 v0, v2
	v_add_f32_e32 v0, v0, v2
	v_pk_fma_f32 v[52:53], v[104:105], v[0:1], v[54:55] op_sel_hi:[1,0,1]
	v_pk_mul_f32 v[118:119], v[52:53], v[120:121] op_sel_hi:[0,1]
	v_pk_fma_f32 v[118:119], v[52:53], v[122:123], v[118:119] op_sel:[1,0,0]
	v_pk_mul_f32 v[126:127], v[110:111], v[126:127] op_sel:[1,0]
	ds_read_b128 v[120:123], v90 offset:0x7400
	v_add_f32_dpp v118, v118, v118 quad_perm:[1,0,3,2] row_mask:0xf bank_mask:0xf bound_ctrl:1
	v_add_f32_dpp v119, v119, v119 quad_perm:[1,0,3,2] row_mask:0xf bank_mask:0xf bound_ctrl:1
	v_pk_fma_f32 v[54:55], v[52:53], v[124:125], v[126:127]
	v_add_f32_dpp v118, v118, v118 quad_perm:[2,3,0,1] row_mask:0xf bank_mask:0xf bound_ctrl:1
	s_nop 0
	ds_read_b128 v[124:127], v90 offset:0x3400
	v_add_f32_dpp v118, v118, v118 row_half_mirror row_mask:0xf bank_mask:0xf bound_ctrl:1
	s_nop 0
	ds_write2_b32 v93, v1, v119 offset0:216 offset1:252
	v_add_f32_dpp v2, v118, v118 row_mirror row_mask:0xf bank_mask:0xf bound_ctrl:1
	v_add_f32_dpp v118, v118, v118 row_mirror row_mask:0xf bank_mask:0xf bound_ctrl:1
	s_nop 0
	s_waitcnt lgkmcnt(4)
	v_permlane16_swap_b32_e32 v118, v2
	v_add_f32_e32 v118, v118, v2
	v_pk_fma_f32 v[52:53], v[106:107], v[118:119], v[54:55] op_sel_hi:[1,0,1]
	v_pk_mul_f32 v[0:1], v[52:53], v[4:5] op_sel_hi:[0,1]
	v_pk_fma_f32 v[0:1], v[52:53], v[6:7], v[0:1] op_sel:[1,0,0]
	v_pk_mul_f32 v[10:11], v[108:109], v[10:11] op_sel_hi:[0,1]
	ds_read_b128 v[4:7], v90 offset:0x7600
	v_add_f32_dpp v0, v0, v0 quad_perm:[1,0,3,2] row_mask:0xf bank_mask:0xf bound_ctrl:1
	v_add_f32_dpp v1, v1, v1 quad_perm:[1,0,3,2] row_mask:0xf bank_mask:0xf bound_ctrl:1
	v_pk_fma_f32 v[54:55], v[52:53], v[8:9], v[10:11]
	v_add_f32_dpp v0, v0, v0 quad_perm:[2,3,0,1] row_mask:0xf bank_mask:0xf bound_ctrl:1
	s_nop 0
	ds_read_b128 v[8:11], v90 offset:0x3600
	v_add_f32_dpp v0, v0, v0 row_half_mirror row_mask:0xf bank_mask:0xf bound_ctrl:1
	ds_read2st64_b32 v[110:111], v89 offset0:218 offset1:219
	ds_read2st64_b64 v[104:107], v88 offset0:90 offset1:91
	v_add_f32_dpp v2, v0, v0 row_mirror row_mask:0xf bank_mask:0xf bound_ctrl:1
	v_add_f32_dpp v0, v0, v0 row_mirror row_mask:0xf bank_mask:0xf bound_ctrl:1
	v_add_u32_e32 v93, 0x480, v93
	s_waitcnt lgkmcnt(7)
	v_permlane16_swap_b32_e32 v0, v2
	v_add_f32_e32 v0, v0, v2
	v_pk_fma_f32 v[52:53], v[100:101], v[0:1], v[54:55] op_sel_hi:[1,0,1]
	v_pk_mul_f32 v[118:119], v[52:53], v[112:113] op_sel_hi:[0,1]
	v_pk_fma_f32 v[118:119], v[52:53], v[114:115], v[118:119] op_sel:[1,0,0]
	v_pk_mul_f32 v[98:99], v[108:109], v[98:99] op_sel:[1,0]
	ds_read_b128 v[112:115], v90 offset:0x7800
	v_add_f32_dpp v118, v118, v118 quad_perm:[1,0,3,2] row_mask:0xf bank_mask:0xf bound_ctrl:1
	v_add_f32_dpp v119, v119, v119 quad_perm:[1,0,3,2] row_mask:0xf bank_mask:0xf bound_ctrl:1
	v_pk_fma_f32 v[54:55], v[52:53], v[96:97], v[98:99]
	v_add_f32_dpp v118, v118, v118 quad_perm:[2,3,0,1] row_mask:0xf bank_mask:0xf bound_ctrl:1
	s_nop 0
	ds_read_b128 v[96:99], v90 offset:0x3800
	v_add_f32_dpp v118, v118, v118 row_half_mirror row_mask:0xf bank_mask:0xf bound_ctrl:1
	s_nop 0
	ds_write2_b32 v93, v1, v119 offset0:0 offset1:36
	v_add_f32_dpp v2, v118, v118 row_mirror row_mask:0xf bank_mask:0xf bound_ctrl:1
	v_add_f32_dpp v118, v118, v118 row_mirror row_mask:0xf bank_mask:0xf bound_ctrl:1
	s_nop 0
	s_waitcnt lgkmcnt(4)
	v_permlane16_swap_b32_e32 v118, v2
	v_add_f32_e32 v118, v118, v2
	v_pk_fma_f32 v[52:53], v[102:103], v[118:119], v[54:55] op_sel_hi:[1,0,1]
	v_pk_mul_f32 v[0:1], v[52:53], v[120:121] op_sel_hi:[0,1]
	v_pk_fma_f32 v[0:1], v[52:53], v[122:123], v[0:1] op_sel:[1,0,0]
	v_pk_mul_f32 v[126:127], v[110:111], v[126:127] op_sel_hi:[0,1]
	ds_read_b128 v[120:123], v90 offset:0x7a00
	v_add_f32_dpp v0, v0, v0 quad_perm:[1,0,3,2] row_mask:0xf bank_mask:0xf bound_ctrl:1
	v_add_f32_dpp v1, v1, v1 quad_perm:[1,0,3,2] row_mask:0xf bank_mask:0xf bound_ctrl:1
	v_pk_fma_f32 v[54:55], v[52:53], v[124:125], v[126:127]
	v_add_f32_dpp v0, v0, v0 quad_perm:[2,3,0,1] row_mask:0xf bank_mask:0xf bound_ctrl:1
	s_nop 0
	ds_read_b128 v[124:127], v90 offset:0x3a00
	v_add_f32_dpp v0, v0, v0 row_half_mirror row_mask:0xf bank_mask:0xf bound_ctrl:1
	ds_read2st64_b32 v[108:109], v89 offset0:220 offset1:221
	ds_read2st64_b64 v[100:103], v88 offset0:92 offset1:93
	v_add_f32_dpp v2, v0, v0 row_mirror row_mask:0xf bank_mask:0xf bound_ctrl:1
	v_add_f32_dpp v0, v0, v0 row_mirror row_mask:0xf bank_mask:0xf bound_ctrl:1
	s_nop 0
	s_waitcnt lgkmcnt(7)
	v_permlane16_swap_b32_e32 v0, v2
	v_add_f32_e32 v0, v0, v2
	v_pk_fma_f32 v[52:53], v[104:105], v[0:1], v[54:55] op_sel_hi:[1,0,1]
	v_pk_mul_f32 v[118:119], v[52:53], v[4:5] op_sel_hi:[0,1]
	v_pk_fma_f32 v[118:119], v[52:53], v[6:7], v[118:119] op_sel:[1,0,0]
	v_pk_mul_f32 v[10:11], v[110:111], v[10:11] op_sel:[1,0]
	ds_read_b128 v[4:7], v90 offset:0x7c00
	v_add_f32_dpp v118, v118, v118 quad_perm:[1,0,3,2] row_mask:0xf bank_mask:0xf bound_ctrl:1
	v_add_f32_dpp v119, v119, v119 quad_perm:[1,0,3,2] row_mask:0xf bank_mask:0xf bound_ctrl:1
	v_pk_fma_f32 v[54:55], v[52:53], v[8:9], v[10:11]
	v_add_f32_dpp v118, v118, v118 quad_perm:[2,3,0,1] row_mask:0xf bank_mask:0xf bound_ctrl:1
	s_nop 0
	ds_read_b128 v[8:11], v90 offset:0x3c00
	v_add_f32_dpp v118, v118, v118 row_half_mirror row_mask:0xf bank_mask:0xf bound_ctrl:1
	s_nop 0
	ds_write2_b32 v93, v1, v119 offset0:72 offset1:108
	v_add_f32_dpp v2, v118, v118 row_mirror row_mask:0xf bank_mask:0xf bound_ctrl:1
	v_add_f32_dpp v118, v118, v118 row_mirror row_mask:0xf bank_mask:0xf bound_ctrl:1
	s_nop 0
	s_waitcnt lgkmcnt(4)
	v_permlane16_swap_b32_e32 v118, v2
	v_add_f32_e32 v118, v118, v2
	v_pk_fma_f32 v[52:53], v[106:107], v[118:119], v[54:55] op_sel_hi:[1,0,1]
	v_pk_mul_f32 v[0:1], v[52:53], v[112:113] op_sel_hi:[0,1]
	v_pk_fma_f32 v[0:1], v[52:53], v[114:115], v[0:1] op_sel:[1,0,0]
	v_pk_mul_f32 v[98:99], v[108:109], v[98:99] op_sel_hi:[0,1]
	ds_read_b128 v[112:115], v90 offset:0x7e00
	v_add_f32_dpp v0, v0, v0 quad_perm:[1,0,3,2] row_mask:0xf bank_mask:0xf bound_ctrl:1
	v_add_f32_dpp v1, v1, v1 quad_perm:[1,0,3,2] row_mask:0xf bank_mask:0xf bound_ctrl:1
	v_pk_fma_f32 v[54:55], v[52:53], v[96:97], v[98:99]
	v_add_f32_dpp v0, v0, v0 quad_perm:[2,3,0,1] row_mask:0xf bank_mask:0xf bound_ctrl:1
	s_nop 0
	ds_read_b128 v[96:99], v90 offset:0x3e00
	v_add_f32_dpp v0, v0, v0 row_half_mirror row_mask:0xf bank_mask:0xf bound_ctrl:1
	ds_read2st64_b32 v[110:111], v89 offset0:222 offset1:223
	ds_read2st64_b64 v[104:107], v88 offset0:94 offset1:95
	v_add_f32_dpp v2, v0, v0 row_mirror row_mask:0xf bank_mask:0xf bound_ctrl:1
	v_add_f32_dpp v0, v0, v0 row_mirror row_mask:0xf bank_mask:0xf bound_ctrl:1
	s_nop 0
	s_waitcnt lgkmcnt(7)
	v_permlane16_swap_b32_e32 v0, v2
	v_add_f32_e32 v0, v0, v2
	v_pk_fma_f32 v[52:53], v[100:101], v[0:1], v[54:55] op_sel_hi:[1,0,1]
	v_pk_mul_f32 v[118:119], v[52:53], v[120:121] op_sel_hi:[0,1]
	v_pk_fma_f32 v[118:119], v[52:53], v[122:123], v[118:119] op_sel:[1,0,0]
	v_pk_mul_f32 v[126:127], v[108:109], v[126:127] op_sel:[1,0]
	s_nop 0
	v_add_f32_dpp v118, v118, v118 quad_perm:[1,0,3,2] row_mask:0xf bank_mask:0xf bound_ctrl:1
	v_add_f32_dpp v119, v119, v119 quad_perm:[1,0,3,2] row_mask:0xf bank_mask:0xf bound_ctrl:1
	v_pk_fma_f32 v[54:55], v[52:53], v[124:125], v[126:127]
	v_add_f32_dpp v118, v118, v118 quad_perm:[2,3,0,1] row_mask:0xf bank_mask:0xf bound_ctrl:1
	s_nop 0
	s_nop 0
	v_add_f32_dpp v118, v118, v118 row_half_mirror row_mask:0xf bank_mask:0xf bound_ctrl:1
	s_nop 0
	ds_write2_b32 v93, v1, v119 offset0:144 offset1:180
	v_add_f32_dpp v2, v118, v118 row_mirror row_mask:0xf bank_mask:0xf bound_ctrl:1
	v_add_f32_dpp v118, v118, v118 row_mirror row_mask:0xf bank_mask:0xf bound_ctrl:1
	s_nop 0
	s_waitcnt lgkmcnt(2)
	v_permlane16_swap_b32_e32 v118, v2
	v_add_f32_e32 v118, v118, v2
	v_pk_fma_f32 v[52:53], v[102:103], v[118:119], v[54:55] op_sel_hi:[1,0,1]
	v_pk_mul_f32 v[0:1], v[52:53], v[4:5] op_sel_hi:[0,1]
	v_pk_fma_f32 v[0:1], v[52:53], v[6:7], v[0:1] op_sel:[1,0,0]
	v_pk_mul_f32 v[10:11], v[110:111], v[10:11] op_sel_hi:[0,1]
	s_nop 0
	v_add_f32_dpp v0, v0, v0 quad_perm:[1,0,3,2] row_mask:0xf bank_mask:0xf bound_ctrl:1
	v_add_f32_dpp v1, v1, v1 quad_perm:[1,0,3,2] row_mask:0xf bank_mask:0xf bound_ctrl:1
	v_pk_fma_f32 v[54:55], v[52:53], v[8:9], v[10:11]
	v_add_f32_dpp v0, v0, v0 quad_perm:[2,3,0,1] row_mask:0xf bank_mask:0xf bound_ctrl:1
	s_nop 0
	s_nop 0
	v_add_f32_dpp v0, v0, v0 row_half_mirror row_mask:0xf bank_mask:0xf bound_ctrl:1
	s_nop 0
	s_nop 0
	v_add_f32_dpp v2, v0, v0 row_mirror row_mask:0xf bank_mask:0xf bound_ctrl:1
	v_add_f32_dpp v0, v0, v0 row_mirror row_mask:0xf bank_mask:0xf bound_ctrl:1
	s_nop 0
	s_waitcnt lgkmcnt(1)
	v_permlane16_swap_b32_e32 v0, v2
	v_add_f32_e32 v0, v0, v2
	v_pk_fma_f32 v[52:53], v[104:105], v[0:1], v[54:55] op_sel_hi:[1,0,1]
	v_pk_mul_f32 v[118:119], v[52:53], v[112:113] op_sel_hi:[0,1]
	v_pk_fma_f32 v[118:119], v[52:53], v[114:115], v[118:119] op_sel:[1,0,0]
	v_pk_mul_f32 v[98:99], v[110:111], v[98:99] op_sel:[1,0]
	s_nop 0
	v_add_f32_dpp v118, v118, v118 quad_perm:[1,0,3,2] row_mask:0xf bank_mask:0xf bound_ctrl:1
	v_add_f32_dpp v119, v119, v119 quad_perm:[1,0,3,2] row_mask:0xf bank_mask:0xf bound_ctrl:1
	v_pk_fma_f32 v[54:55], v[52:53], v[96:97], v[98:99]
	v_add_f32_dpp v118, v118, v118 quad_perm:[2,3,0,1] row_mask:0xf bank_mask:0xf bound_ctrl:1
	s_nop 0
	s_nop 0
	v_add_f32_dpp v118, v118, v118 row_half_mirror row_mask:0xf bank_mask:0xf bound_ctrl:1
	s_nop 0
	ds_write2_b32 v93, v1, v119 offset0:216 offset1:252
	v_add_f32_dpp v2, v118, v118 row_mirror row_mask:0xf bank_mask:0xf bound_ctrl:1
	v_add_f32_dpp v118, v118, v118 row_mirror row_mask:0xf bank_mask:0xf bound_ctrl:1
	s_nop 0
	s_nop 0
	v_permlane16_swap_b32_e32 v118, v2
	v_add_f32_e32 v118, v118, v2
	v_pk_fma_f32 v[52:53], v[106:107], v[118:119], v[54:55] op_sel_hi:[1,0,1]
